# GLA prep: gate-logit dot products as DPP row-broadcast fmacs from registers (4 LDS reads per item instead of 64 broadcast reads, no operand shuffling moves)
# baseline (speedup 1.0000x reference)
.LBB0_985:
	s_mov_b64 s[4:5], s[0:1]
	v_mov_b32_e32 v18, v226
	s_load_dwordx4 s[12:15], s[4:5], 0x28
	s_load_dwordx2 s[50:51], s[4:5], 0x58
	s_bfe_u32 s31, s82, 0x20005
	s_and_b32 s6, s26, 0x7c0
	v_and_b32_e32 v19, 0x7f, v18
	s_waitcnt lgkmcnt(0)
	s_add_u32 s4, s12, s86
	s_addc_u32 s5, s13, s87
	s_lshl_b32 s7, s31, 9
	s_add_u32 s4, s4, s7
	s_addc_u32 s5, s5, 0
	v_lshlrev_b32_e32 v208, 2, v19
	v_lshl_add_u64 v[0:1], s[4:5], 0, v[208:209]
	v_add_co_u32_e32 v2, vcc, s34, v0
	global_load_dword v6, v208, s[4:5]
	global_load_dword v8, v208, s[4:5] offset:2048
	v_addc_co_u32_e32 v3, vcc, 0, v1, vcc
	v_add_co_u32_e32 v4, vcc, s17, v0
	s_movk_i32 s4, 0x5000
	s_nop 0
	v_addc_co_u32_e32 v5, vcc, 0, v1, vcc
	global_load_dword v12, v[4:5], off offset:-4096
	global_load_dword v10, v[2:3], off offset:2048
	global_load_dword v7, v[4:5], off
	global_load_dword v9, v[4:5], off offset:2048
	v_add_co_u32_e32 v2, vcc, s35, v0
	v_ashrrev_i32_e32 v58, 3, v18
	s_nop 0
	v_addc_co_u32_e32 v3, vcc, 0, v1, vcc
	v_add_co_u32_e32 v4, vcc, s20, v0
	v_mov_b32_e32 v25, v209
	s_nop 0
	v_addc_co_u32_e32 v5, vcc, 0, v1, vcc
	v_add_co_u32_e32 v14, vcc, s4, v0
	s_movk_i32 s4, 0x7000
	s_nop 0
	v_addc_co_u32_e32 v15, vcc, 0, v1, vcc
	v_add_co_u32_e32 v20, vcc, s21, v0
	global_load_dword v13, v[4:5], off offset:-4096
	global_load_dword v11, v[2:3], off offset:2048
	s_nop 0
	global_load_dword v2, v[4:5], off
	s_nop 0
	global_load_dword v4, v[4:5], off offset:2048
	v_addc_co_u32_e32 v21, vcc, 0, v1, vcc
	v_add_co_u32_e32 v0, vcc, s4, v0
	s_add_u32 s4, s50, 0xb400000
	s_addc_u32 s5, s51, 0
	s_and_b32 s12, s22, 0xfffff800
	s_or_b32 s12, s12, s6
	global_load_dword v16, v[20:21], off offset:-4096
	s_nop 0
	global_load_dword v14, v[14:15], off offset:2048
	s_nop 0
	global_load_dword v3, v[20:21], off
	global_load_dword v5, v[20:21], off offset:2048
	v_addc_co_u32_e32 v1, vcc, 0, v1, vcc
	s_add_u32 s6, s14, s88
	v_add_u32_e32 v20, s12, v58
	global_load_dword v17, v[0:1], off
	global_load_dword v15, v[0:1], off offset:2048
	s_addc_u32 s13, s15, s89
	v_lshlrev_b32_e32 v0, 1, v18
	v_ashrrev_i32_e32 v21, 31, v20
	s_add_u32 s6, s6, s7
	v_and_b32_e32 v59, 14, v0
	v_lshlrev_b64 v[20:21], 8, v[20:21]
	s_addc_u32 s7, s13, 0
	v_lshl_add_u64 v[20:21], s[4:5], 0, v[20:21]
	v_lshlrev_b32_e32 v24, 1, v59
	global_load_dword v22, v208, s[6:7]
	v_lshl_add_u64 v[20:21], v[20:21], 0, v[24:25]
	s_mov_b32 s6, 0x5000000
	v_add_co_u32_e32 v20, vcc, s6, v20
	v_ashrrev_i32_e32 v1, 7, v18
	s_nop 0
	v_addc_co_u32_e32 v21, vcc, 0, v21, vcc
	global_load_dword v60, v[20:21], off
	v_lshlrev_b32_e32 v0, 4, v1
	v_add_u32_e32 v20, s12, v0
	s_lshl_b32 s6, s31, 21
	v_ashrrev_i32_e32 v21, 31, v20
	v_or_b32_e32 v28, 1, v20
	s_add_u32 s6, s4, s6
	v_lshlrev_b64 v[24:25], 8, v[20:21]
	v_ashrrev_i32_e32 v29, 31, v28
	v_or_b32_e32 v30, 2, v20
	v_or_b32_e32 v32, 3, v20
	v_or_b32_e32 v34, 4, v20
	v_or_b32_e32 v36, 5, v20
	v_or_b32_e32 v38, 6, v20
	v_or_b32_e32 v40, 7, v20
	v_or_b32_e32 v42, 8, v20
	v_or_b32_e32 v44, 9, v20
	v_or_b32_e32 v46, 10, v20
	v_or_b32_e32 v48, 11, v20
	v_or_b32_e32 v50, 12, v20
	v_or_b32_e32 v52, 13, v20
	v_or_b32_e32 v54, 14, v20
	v_or_b32_e32 v20, 15, v20
	s_addc_u32 s7, s5, 0
	v_lshlrev_b64 v[28:29], 8, v[28:29]
	v_ashrrev_i32_e32 v21, 31, v20
	v_lshlrev_b32_e32 v26, 1, v19
	v_mov_b32_e32 v27, v209
	v_lshl_add_u64 v[28:29], s[6:7], 0, v[28:29]
	v_lshlrev_b64 v[20:21], 8, v[20:21]
	v_lshl_add_u64 v[28:29], v[28:29], 0, v[26:27]
	v_lshl_add_u64 v[20:21], s[6:7], 0, v[20:21]
	v_lshl_add_u64 v[24:25], s[6:7], 0, v[24:25]
	v_ashrrev_i32_e32 v31, 31, v30
	v_lshl_add_u64 v[56:57], v[20:21], 0, v[26:27]
	v_add_co_u32_e32 v20, vcc, s37, v28
	v_lshl_add_u64 v[24:25], v[24:25], 0, v[26:27]
	v_lshlrev_b64 v[30:31], 8, v[30:31]
	v_addc_co_u32_e32 v21, vcc, 0, v29, vcc
	v_lshl_add_u64 v[30:31], s[6:7], 0, v[30:31]
	v_ashrrev_i32_e32 v33, 31, v32
	global_load_ushort v23, v[20:21], off
	v_add_co_u32_e32 v20, vcc, s37, v24
	v_lshl_add_u64 v[30:31], v[30:31], 0, v[26:27]
	v_lshlrev_b64 v[32:33], 8, v[32:33]
	v_addc_co_u32_e32 v21, vcc, 0, v25, vcc
	v_lshl_add_u64 v[32:33], s[6:7], 0, v[32:33]
	v_ashrrev_i32_e32 v35, 31, v34
	global_load_ushort v24, v[20:21], off
	v_add_co_u32_e32 v20, vcc, s37, v30
	v_lshl_add_u64 v[32:33], v[32:33], 0, v[26:27]
	v_lshlrev_b64 v[34:35], 8, v[34:35]
	v_ashrrev_i32_e32 v37, 31, v36
	v_ashrrev_i32_e32 v39, 31, v38
	v_ashrrev_i32_e32 v41, 31, v40
	v_ashrrev_i32_e32 v43, 31, v42
	v_ashrrev_i32_e32 v45, 31, v44
	v_ashrrev_i32_e32 v47, 31, v46
	v_ashrrev_i32_e32 v49, 31, v48
	v_ashrrev_i32_e32 v51, 31, v50
	v_ashrrev_i32_e32 v53, 31, v52
	v_ashrrev_i32_e32 v55, 31, v54
	v_addc_co_u32_e32 v21, vcc, 0, v31, vcc
	v_lshl_add_u64 v[34:35], s[6:7], 0, v[34:35]
	v_lshlrev_b64 v[36:37], 8, v[36:37]
	v_lshlrev_b64 v[38:39], 8, v[38:39]
	v_lshlrev_b64 v[40:41], 8, v[40:41]
	v_lshlrev_b64 v[42:43], 8, v[42:43]
	v_lshlrev_b64 v[44:45], 8, v[44:45]
	v_lshlrev_b64 v[46:47], 8, v[46:47]
	v_lshlrev_b64 v[48:49], 8, v[48:49]
	v_lshlrev_b64 v[50:51], 8, v[50:51]
	v_lshlrev_b64 v[52:53], 8, v[52:53]
	v_lshlrev_b64 v[54:55], 8, v[54:55]
	global_load_ushort v25, v[20:21], off
	v_add_co_u32_e32 v20, vcc, s37, v32
	v_lshl_add_u64 v[34:35], v[34:35], 0, v[26:27]
	v_lshl_add_u64 v[36:37], s[6:7], 0, v[36:37]
	v_lshl_add_u64 v[38:39], s[6:7], 0, v[38:39]
	v_lshl_add_u64 v[40:41], s[6:7], 0, v[40:41]
	v_lshl_add_u64 v[42:43], s[6:7], 0, v[42:43]
	v_lshl_add_u64 v[44:45], s[6:7], 0, v[44:45]
	v_lshl_add_u64 v[46:47], s[6:7], 0, v[46:47]
	v_lshl_add_u64 v[48:49], s[6:7], 0, v[48:49]
	v_lshl_add_u64 v[50:51], s[6:7], 0, v[50:51]
	v_lshl_add_u64 v[52:53], s[6:7], 0, v[52:53]
	v_lshl_add_u64 v[54:55], s[6:7], 0, v[54:55]
	v_addc_co_u32_e32 v21, vcc, 0, v33, vcc
	v_lshl_add_u64 v[36:37], v[36:37], 0, v[26:27]
	v_lshl_add_u64 v[38:39], v[38:39], 0, v[26:27]
	v_lshl_add_u64 v[40:41], v[40:41], 0, v[26:27]
	v_lshl_add_u64 v[42:43], v[42:43], 0, v[26:27]
	v_lshl_add_u64 v[44:45], v[44:45], 0, v[26:27]
	v_lshl_add_u64 v[46:47], v[46:47], 0, v[26:27]
	v_lshl_add_u64 v[48:49], v[48:49], 0, v[26:27]
	v_lshl_add_u64 v[50:51], v[50:51], 0, v[26:27]
	v_lshl_add_u64 v[52:53], v[52:53], 0, v[26:27]
	v_lshl_add_u64 v[54:55], v[54:55], 0, v[26:27]
	global_load_ushort v26, v[20:21], off
	v_add_co_u32_e32 v20, vcc, s37, v34
	s_mov_b32 s5, 0xbfb8aa3b
	s_nop 0
	v_addc_co_u32_e32 v21, vcc, 0, v35, vcc
	global_load_ushort v27, v[20:21], off
	v_add_co_u32_e32 v20, vcc, s37, v36
	s_mov_b32 s12, 0x7f800000
	s_nop 0
	v_addc_co_u32_e32 v21, vcc, 0, v37, vcc
	global_load_ushort v28, v[20:21], off
	v_add_co_u32_e32 v20, vcc, s37, v38
	v_lshlrev_b32_e32 v37, 6, v58
	s_nop 0
	v_addc_co_u32_e32 v21, vcc, 0, v39, vcc
	global_load_ushort v29, v[20:21], off
	v_add_co_u32_e32 v20, vcc, s37, v40
	s_mov_b32 s4, 0x3d800000
	s_nop 0
	v_addc_co_u32_e32 v21, vcc, 0, v41, vcc
	global_load_ushort v30, v[20:21], off
	v_add_co_u32_e32 v20, vcc, s37, v42
	s_nop 1
	v_addc_co_u32_e32 v21, vcc, 0, v43, vcc
	global_load_ushort v31, v[20:21], off
	v_add_co_u32_e32 v20, vcc, s37, v44
	s_nop 1
	v_addc_co_u32_e32 v21, vcc, 0, v45, vcc
	global_load_ushort v32, v[20:21], off
	v_add_co_u32_e32 v20, vcc, s37, v46
	s_nop 1
	v_addc_co_u32_e32 v21, vcc, 0, v47, vcc
	global_load_ushort v33, v[20:21], off
	v_add_co_u32_e32 v20, vcc, s37, v48
	s_nop 1
	v_addc_co_u32_e32 v21, vcc, 0, v49, vcc
	global_load_ushort v34, v[20:21], off
	v_add_co_u32_e32 v20, vcc, s37, v50
	s_nop 1
	v_addc_co_u32_e32 v21, vcc, 0, v51, vcc
	global_load_ushort v35, v[20:21], off
	v_add_co_u32_e32 v20, vcc, s37, v52
	s_nop 1
	v_addc_co_u32_e32 v21, vcc, 0, v53, vcc
	global_load_ushort v36, v[20:21], off
	v_add_co_u32_e32 v20, vcc, s37, v54
	s_nop 1
	v_addc_co_u32_e32 v21, vcc, 0, v55, vcc
	v_add_co_u32_e32 v38, vcc, s37, v56
	global_load_ushort v20, v[20:21], off
	s_nop 0
	v_addc_co_u32_e32 v39, vcc, 0, v57, vcc
	global_load_ushort v21, v[38:39], off
	v_lshlrev_b32_e32 v39, 2, v59
	s_waitcnt vmcnt(0)
	v_lshlrev_b32_e32 v38, 16, v60
	v_add3_u32 v37, 0, v37, v39
	v_and_b32_e32 v39, 0xffff0000, v60
	s_barrier
	ds_write_b64 v37, v[38:39]
	v_lshl_add_u32 v38, v1, 10, 0
	s_waitcnt lgkmcnt(0)
	s_barrier
	v_and_b32_e32 v80, 15, v226
	v_lshl_add_u32 v80, v80, 6, v38
	ds_read_b128 v[64:67], v80
	ds_read_b128 v[68:71], v80 offset:16
	ds_read_b128 v[72:75], v80 offset:32
	ds_read_b128 v[76:79], v80 offset:48
	s_waitcnt lgkmcnt(0)
	s_waitcnt lgkmcnt(3)
	s_waitcnt lgkmcnt(2)
	v_mov_b32_e32 v81, v22
	v_fmac_f32_dpp v81, v64, v6 row_newbcast:0 row_mask:0xf bank_mask:0xf
	v_fmac_f32_dpp v81, v65, v8 row_newbcast:0 row_mask:0xf bank_mask:0xf
	v_fmac_f32_dpp v81, v66, v12 row_newbcast:0 row_mask:0xf bank_mask:0xf
	v_fmac_f32_dpp v81, v67, v10 row_newbcast:0 row_mask:0xf bank_mask:0xf
	v_fmac_f32_dpp v81, v68, v7 row_newbcast:0 row_mask:0xf bank_mask:0xf
	v_fmac_f32_dpp v81, v69, v9 row_newbcast:0 row_mask:0xf bank_mask:0xf
	v_fmac_f32_dpp v81, v70, v13 row_newbcast:0 row_mask:0xf bank_mask:0xf
	v_fmac_f32_dpp v81, v71, v11 row_newbcast:0 row_mask:0xf bank_mask:0xf
	v_fmac_f32_dpp v81, v72, v2 row_newbcast:0 row_mask:0xf bank_mask:0xf
	v_fmac_f32_dpp v81, v73, v4 row_newbcast:0 row_mask:0xf bank_mask:0xf
	v_fmac_f32_dpp v81, v74, v16 row_newbcast:0 row_mask:0xf bank_mask:0xf
	v_fmac_f32_dpp v81, v75, v14 row_newbcast:0 row_mask:0xf bank_mask:0xf
	v_fmac_f32_dpp v81, v76, v3 row_newbcast:0 row_mask:0xf bank_mask:0xf
	v_fmac_f32_dpp v81, v77, v5 row_newbcast:0 row_mask:0xf bank_mask:0xf
	v_fmac_f32_dpp v81, v78, v17 row_newbcast:0 row_mask:0xf bank_mask:0xf
	v_fmac_f32_dpp v81, v79, v15 row_newbcast:0 row_mask:0xf bank_mask:0xf
	s_nop 0
	s_waitcnt lgkmcnt(0)
	s_nop 0
	s_nop 0
	v_mov_b32_e32 v37, v81
	v_min_f32_e32 v39, 0, v37
	v_mul_f32_e64 v37, |v37|, s5
	v_exp_f32_e32 v37, v37
	s_nop 0
	v_add_f32_e32 v37, 1.0, v37
	v_cmp_gt_f32_e32 vcc, s37, v37
	s_nop 1
	v_cndmask_b32_e64 v40, 0, 32, vcc
	v_ldexp_f32 v37, v37, v40
	v_log_f32_e32 v37, v37
	s_nop 0
	v_mul_f32_e32 v40, 0x3f317217, v37
	v_fma_f32 v40, v37, s2, -v40
	v_fmac_f32_e32 v40, 0x3377d1cf, v37
	v_fmac_f32_e32 v40, 0x3f317217, v37
	v_cmp_lt_f32_e64 s[6:7], |v37|, s12
	s_nop 1
	v_cndmask_b32_e64 v37, v37, v40, s[6:7]
	v_cndmask_b32_e32 v40, 0, v232, vcc
	v_sub_f32_e32 v37, v37, v40
	v_sub_f32_e32 v37, v39, v37
	v_fma_f32 v37, v37, s4, 0
	s_movk_i32 s4, 0x80
	s_waitcnt lgkmcnt(1)
	s_waitcnt lgkmcnt(0)
	v_mov_b32_e32 v81, v22
	v_fmac_f32_dpp v81, v64, v6 row_newbcast:1 row_mask:0xf bank_mask:0xf
	v_fmac_f32_dpp v81, v65, v8 row_newbcast:1 row_mask:0xf bank_mask:0xf
	v_fmac_f32_dpp v81, v66, v12 row_newbcast:1 row_mask:0xf bank_mask:0xf
	v_fmac_f32_dpp v81, v67, v10 row_newbcast:1 row_mask:0xf bank_mask:0xf
	v_fmac_f32_dpp v81, v68, v7 row_newbcast:1 row_mask:0xf bank_mask:0xf
	v_fmac_f32_dpp v81, v69, v9 row_newbcast:1 row_mask:0xf bank_mask:0xf
	v_fmac_f32_dpp v81, v70, v13 row_newbcast:1 row_mask:0xf bank_mask:0xf
	v_fmac_f32_dpp v81, v71, v11 row_newbcast:1 row_mask:0xf bank_mask:0xf
	v_fmac_f32_dpp v81, v72, v2 row_newbcast:1 row_mask:0xf bank_mask:0xf
	v_fmac_f32_dpp v81, v73, v4 row_newbcast:1 row_mask:0xf bank_mask:0xf
	v_fmac_f32_dpp v81, v74, v16 row_newbcast:1 row_mask:0xf bank_mask:0xf
	v_fmac_f32_dpp v81, v75, v14 row_newbcast:1 row_mask:0xf bank_mask:0xf
	v_fmac_f32_dpp v81, v76, v3 row_newbcast:1 row_mask:0xf bank_mask:0xf
	v_fmac_f32_dpp v81, v77, v5 row_newbcast:1 row_mask:0xf bank_mask:0xf
	v_fmac_f32_dpp v81, v78, v17 row_newbcast:1 row_mask:0xf bank_mask:0xf
	v_fmac_f32_dpp v81, v79, v15 row_newbcast:1 row_mask:0xf bank_mask:0xf
	s_nop 0
	s_waitcnt lgkmcnt(1)
	s_waitcnt lgkmcnt(0)
	s_nop 0
	v_mov_b32_e32 v39, v81
	v_min_f32_e32 v40, 0, v39
	v_mul_f32_e64 v39, |v39|, s5
	v_exp_f32_e32 v39, v39
	s_nop 0
	v_add_f32_e32 v39, 1.0, v39
	v_cmp_gt_f32_e32 vcc, s37, v39
	s_nop 1
	v_cndmask_b32_e64 v41, 0, 32, vcc
	v_ldexp_f32 v39, v39, v41
	v_log_f32_e32 v39, v39
	s_nop 0
	v_mul_f32_e32 v41, 0x3f317217, v39
	v_fma_f32 v41, v39, s2, -v41
	v_fmac_f32_e32 v41, 0x3377d1cf, v39
	v_fmac_f32_e32 v41, 0x3f317217, v39
	v_cmp_lt_f32_e64 s[6:7], |v39|, s12
	s_nop 1
	v_cndmask_b32_e64 v39, v39, v41, s[6:7]
	v_cndmask_b32_e32 v41, 0, v232, vcc
	v_sub_f32_e32 v39, v39, v41
	v_sub_f32_e32 v39, v40, v39
	v_fmamk_f32 v39, v39, 0x3d800000, v37
	s_waitcnt lgkmcnt(1)
	s_waitcnt lgkmcnt(0)
	v_mov_b32_e32 v81, v22
	v_fmac_f32_dpp v81, v64, v6 row_newbcast:2 row_mask:0xf bank_mask:0xf
	v_fmac_f32_dpp v81, v65, v8 row_newbcast:2 row_mask:0xf bank_mask:0xf
	v_fmac_f32_dpp v81, v66, v12 row_newbcast:2 row_mask:0xf bank_mask:0xf
	v_fmac_f32_dpp v81, v67, v10 row_newbcast:2 row_mask:0xf bank_mask:0xf
	v_fmac_f32_dpp v81, v68, v7 row_newbcast:2 row_mask:0xf bank_mask:0xf
	v_fmac_f32_dpp v81, v69, v9 row_newbcast:2 row_mask:0xf bank_mask:0xf
	v_fmac_f32_dpp v81, v70, v13 row_newbcast:2 row_mask:0xf bank_mask:0xf
	v_fmac_f32_dpp v81, v71, v11 row_newbcast:2 row_mask:0xf bank_mask:0xf
	v_fmac_f32_dpp v81, v72, v2 row_newbcast:2 row_mask:0xf bank_mask:0xf
	v_fmac_f32_dpp v81, v73, v4 row_newbcast:2 row_mask:0xf bank_mask:0xf
	v_fmac_f32_dpp v81, v74, v16 row_newbcast:2 row_mask:0xf bank_mask:0xf
	v_fmac_f32_dpp v81, v75, v14 row_newbcast:2 row_mask:0xf bank_mask:0xf
	v_fmac_f32_dpp v81, v76, v3 row_newbcast:2 row_mask:0xf bank_mask:0xf
	v_fmac_f32_dpp v81, v77, v5 row_newbcast:2 row_mask:0xf bank_mask:0xf
	v_fmac_f32_dpp v81, v78, v17 row_newbcast:2 row_mask:0xf bank_mask:0xf
	v_fmac_f32_dpp v81, v79, v15 row_newbcast:2 row_mask:0xf bank_mask:0xf
	s_nop 0
	s_waitcnt lgkmcnt(1)
	s_waitcnt lgkmcnt(0)
	s_nop 0
	v_mov_b32_e32 v40, v81
	v_min_f32_e32 v41, 0, v40
	v_mul_f32_e64 v40, |v40|, s5
	v_exp_f32_e32 v40, v40
	s_nop 0
	v_add_f32_e32 v40, 1.0, v40
	v_cmp_gt_f32_e32 vcc, s37, v40
	s_nop 1
	v_cndmask_b32_e64 v42, 0, 32, vcc
	v_ldexp_f32 v40, v40, v42
	v_log_f32_e32 v40, v40
	s_nop 0
	v_mul_f32_e32 v42, 0x3f317217, v40
	v_fma_f32 v42, v40, s2, -v42
	v_fmac_f32_e32 v42, 0x3377d1cf, v40
	v_fmac_f32_e32 v42, 0x3f317217, v40
	v_cmp_lt_f32_e64 s[6:7], |v40|, s12
	s_nop 1
	v_cndmask_b32_e64 v40, v40, v42, s[6:7]
	v_cndmask_b32_e32 v42, 0, v232, vcc
	v_sub_f32_e32 v40, v40, v42
	v_sub_f32_e32 v40, v41, v40
	v_fmamk_f32 v40, v40, 0x3d800000, v39
	s_waitcnt lgkmcnt(1)
	s_waitcnt lgkmcnt(0)
	v_mov_b32_e32 v81, v22
	v_fmac_f32_dpp v81, v64, v6 row_newbcast:3 row_mask:0xf bank_mask:0xf
	v_fmac_f32_dpp v81, v65, v8 row_newbcast:3 row_mask:0xf bank_mask:0xf
	v_fmac_f32_dpp v81, v66, v12 row_newbcast:3 row_mask:0xf bank_mask:0xf
	v_fmac_f32_dpp v81, v67, v10 row_newbcast:3 row_mask:0xf bank_mask:0xf
	v_fmac_f32_dpp v81, v68, v7 row_newbcast:3 row_mask:0xf bank_mask:0xf
	v_fmac_f32_dpp v81, v69, v9 row_newbcast:3 row_mask:0xf bank_mask:0xf
	v_fmac_f32_dpp v81, v70, v13 row_newbcast:3 row_mask:0xf bank_mask:0xf
	v_fmac_f32_dpp v81, v71, v11 row_newbcast:3 row_mask:0xf bank_mask:0xf
	v_fmac_f32_dpp v81, v72, v2 row_newbcast:3 row_mask:0xf bank_mask:0xf
	v_fmac_f32_dpp v81, v73, v4 row_newbcast:3 row_mask:0xf bank_mask:0xf
	v_fmac_f32_dpp v81, v74, v16 row_newbcast:3 row_mask:0xf bank_mask:0xf
	v_fmac_f32_dpp v81, v75, v14 row_newbcast:3 row_mask:0xf bank_mask:0xf
	v_fmac_f32_dpp v81, v76, v3 row_newbcast:3 row_mask:0xf bank_mask:0xf
	v_fmac_f32_dpp v81, v77, v5 row_newbcast:3 row_mask:0xf bank_mask:0xf
	v_fmac_f32_dpp v81, v78, v17 row_newbcast:3 row_mask:0xf bank_mask:0xf
	v_fmac_f32_dpp v81, v79, v15 row_newbcast:3 row_mask:0xf bank_mask:0xf
	s_nop 0
	s_waitcnt lgkmcnt(1)
	s_waitcnt lgkmcnt(0)
	s_nop 0
	v_mov_b32_e32 v41, v81
	v_min_f32_e32 v42, 0, v41
	v_mul_f32_e64 v41, |v41|, s5
	v_exp_f32_e32 v41, v41
	s_nop 0
	v_add_f32_e32 v41, 1.0, v41
	v_cmp_gt_f32_e32 vcc, s37, v41
	s_nop 1
	v_cndmask_b32_e64 v43, 0, 32, vcc
	v_ldexp_f32 v41, v41, v43
	v_log_f32_e32 v41, v41
	s_nop 0
	v_mul_f32_e32 v43, 0x3f317217, v41
	v_fma_f32 v43, v41, s2, -v43
	v_fmac_f32_e32 v43, 0x3377d1cf, v41
	v_fmac_f32_e32 v43, 0x3f317217, v41
	v_cmp_lt_f32_e64 s[6:7], |v41|, s12
	s_nop 1
	v_cndmask_b32_e64 v41, v41, v43, s[6:7]
	v_cndmask_b32_e32 v43, 0, v232, vcc
	v_sub_f32_e32 v41, v41, v43
	v_sub_f32_e32 v41, v42, v41
	v_fmamk_f32 v41, v41, 0x3d800000, v40
	s_waitcnt lgkmcnt(1)
	s_waitcnt lgkmcnt(0)
	v_mov_b32_e32 v81, v22
	v_fmac_f32_dpp v81, v64, v6 row_newbcast:4 row_mask:0xf bank_mask:0xf
	v_fmac_f32_dpp v81, v65, v8 row_newbcast:4 row_mask:0xf bank_mask:0xf
	v_fmac_f32_dpp v81, v66, v12 row_newbcast:4 row_mask:0xf bank_mask:0xf
	v_fmac_f32_dpp v81, v67, v10 row_newbcast:4 row_mask:0xf bank_mask:0xf
	v_fmac_f32_dpp v81, v68, v7 row_newbcast:4 row_mask:0xf bank_mask:0xf
	v_fmac_f32_dpp v81, v69, v9 row_newbcast:4 row_mask:0xf bank_mask:0xf
	v_fmac_f32_dpp v81, v70, v13 row_newbcast:4 row_mask:0xf bank_mask:0xf
	v_fmac_f32_dpp v81, v71, v11 row_newbcast:4 row_mask:0xf bank_mask:0xf
	v_fmac_f32_dpp v81, v72, v2 row_newbcast:4 row_mask:0xf bank_mask:0xf
	v_fmac_f32_dpp v81, v73, v4 row_newbcast:4 row_mask:0xf bank_mask:0xf
	v_fmac_f32_dpp v81, v74, v16 row_newbcast:4 row_mask:0xf bank_mask:0xf
	v_fmac_f32_dpp v81, v75, v14 row_newbcast:4 row_mask:0xf bank_mask:0xf
	v_fmac_f32_dpp v81, v76, v3 row_newbcast:4 row_mask:0xf bank_mask:0xf
	v_fmac_f32_dpp v81, v77, v5 row_newbcast:4 row_mask:0xf bank_mask:0xf
	v_fmac_f32_dpp v81, v78, v17 row_newbcast:4 row_mask:0xf bank_mask:0xf
	v_fmac_f32_dpp v81, v79, v15 row_newbcast:4 row_mask:0xf bank_mask:0xf
	s_nop 0
	s_waitcnt lgkmcnt(1)
	s_waitcnt lgkmcnt(0)
	s_nop 0
	v_mov_b32_e32 v42, v81
	v_min_f32_e32 v43, 0, v42
	v_mul_f32_e64 v42, |v42|, s5
	v_exp_f32_e32 v42, v42
	s_nop 0
	v_add_f32_e32 v42, 1.0, v42
	v_cmp_gt_f32_e32 vcc, s37, v42
	s_nop 1
	v_cndmask_b32_e64 v44, 0, 32, vcc
	v_ldexp_f32 v42, v42, v44
	v_log_f32_e32 v42, v42
	s_nop 0
	v_mul_f32_e32 v44, 0x3f317217, v42
	v_fma_f32 v44, v42, s2, -v44
	v_fmac_f32_e32 v44, 0x3377d1cf, v42
	v_fmac_f32_e32 v44, 0x3f317217, v42
	v_cmp_lt_f32_e64 s[6:7], |v42|, s12
	s_nop 1
	v_cndmask_b32_e64 v42, v42, v44, s[6:7]
	v_cndmask_b32_e32 v44, 0, v232, vcc
	v_sub_f32_e32 v42, v42, v44
	v_sub_f32_e32 v42, v43, v42
	v_fmamk_f32 v42, v42, 0x3d800000, v41
	s_waitcnt lgkmcnt(1)
	s_waitcnt lgkmcnt(0)
	v_mov_b32_e32 v81, v22
	v_fmac_f32_dpp v81, v64, v6 row_newbcast:5 row_mask:0xf bank_mask:0xf
	v_fmac_f32_dpp v81, v65, v8 row_newbcast:5 row_mask:0xf bank_mask:0xf
	v_fmac_f32_dpp v81, v66, v12 row_newbcast:5 row_mask:0xf bank_mask:0xf
	v_fmac_f32_dpp v81, v67, v10 row_newbcast:5 row_mask:0xf bank_mask:0xf
	v_fmac_f32_dpp v81, v68, v7 row_newbcast:5 row_mask:0xf bank_mask:0xf
	v_fmac_f32_dpp v81, v69, v9 row_newbcast:5 row_mask:0xf bank_mask:0xf
	v_fmac_f32_dpp v81, v70, v13 row_newbcast:5 row_mask:0xf bank_mask:0xf
	v_fmac_f32_dpp v81, v71, v11 row_newbcast:5 row_mask:0xf bank_mask:0xf
	v_fmac_f32_dpp v81, v72, v2 row_newbcast:5 row_mask:0xf bank_mask:0xf
	v_fmac_f32_dpp v81, v73, v4 row_newbcast:5 row_mask:0xf bank_mask:0xf
	v_fmac_f32_dpp v81, v74, v16 row_newbcast:5 row_mask:0xf bank_mask:0xf
	v_fmac_f32_dpp v81, v75, v14 row_newbcast:5 row_mask:0xf bank_mask:0xf
	v_fmac_f32_dpp v81, v76, v3 row_newbcast:5 row_mask:0xf bank_mask:0xf
	v_fmac_f32_dpp v81, v77, v5 row_newbcast:5 row_mask:0xf bank_mask:0xf
	v_fmac_f32_dpp v81, v78, v17 row_newbcast:5 row_mask:0xf bank_mask:0xf
	v_fmac_f32_dpp v81, v79, v15 row_newbcast:5 row_mask:0xf bank_mask:0xf
	s_nop 0
	s_waitcnt lgkmcnt(1)
	s_waitcnt lgkmcnt(0)
	s_nop 0
	v_mov_b32_e32 v43, v81
	v_min_f32_e32 v44, 0, v43
	v_mul_f32_e64 v43, |v43|, s5
	v_exp_f32_e32 v43, v43
	s_nop 0
	v_add_f32_e32 v43, 1.0, v43
	v_cmp_gt_f32_e32 vcc, s37, v43
	s_nop 1
	v_cndmask_b32_e64 v45, 0, 32, vcc
	v_ldexp_f32 v43, v43, v45
	v_log_f32_e32 v43, v43
	s_nop 0
	v_mul_f32_e32 v45, 0x3f317217, v43
	v_fma_f32 v45, v43, s2, -v45
	v_fmac_f32_e32 v45, 0x3377d1cf, v43
	v_fmac_f32_e32 v45, 0x3f317217, v43
	v_cmp_lt_f32_e64 s[6:7], |v43|, s12
	s_nop 1
	v_cndmask_b32_e64 v43, v43, v45, s[6:7]
	v_cndmask_b32_e32 v45, 0, v232, vcc
	v_sub_f32_e32 v43, v43, v45
	v_sub_f32_e32 v43, v44, v43
	v_fmamk_f32 v43, v43, 0x3d800000, v42
	s_waitcnt lgkmcnt(1)
	s_waitcnt lgkmcnt(0)
	v_mov_b32_e32 v81, v22
	v_fmac_f32_dpp v81, v64, v6 row_newbcast:6 row_mask:0xf bank_mask:0xf
	v_fmac_f32_dpp v81, v65, v8 row_newbcast:6 row_mask:0xf bank_mask:0xf
	v_fmac_f32_dpp v81, v66, v12 row_newbcast:6 row_mask:0xf bank_mask:0xf
	v_fmac_f32_dpp v81, v67, v10 row_newbcast:6 row_mask:0xf bank_mask:0xf
	v_fmac_f32_dpp v81, v68, v7 row_newbcast:6 row_mask:0xf bank_mask:0xf
	v_fmac_f32_dpp v81, v69, v9 row_newbcast:6 row_mask:0xf bank_mask:0xf
	v_fmac_f32_dpp v81, v70, v13 row_newbcast:6 row_mask:0xf bank_mask:0xf
	v_fmac_f32_dpp v81, v71, v11 row_newbcast:6 row_mask:0xf bank_mask:0xf
	v_fmac_f32_dpp v81, v72, v2 row_newbcast:6 row_mask:0xf bank_mask:0xf
	v_fmac_f32_dpp v81, v73, v4 row_newbcast:6 row_mask:0xf bank_mask:0xf
	v_fmac_f32_dpp v81, v74, v16 row_newbcast:6 row_mask:0xf bank_mask:0xf
	v_fmac_f32_dpp v81, v75, v14 row_newbcast:6 row_mask:0xf bank_mask:0xf
	v_fmac_f32_dpp v81, v76, v3 row_newbcast:6 row_mask:0xf bank_mask:0xf
	v_fmac_f32_dpp v81, v77, v5 row_newbcast:6 row_mask:0xf bank_mask:0xf
	v_fmac_f32_dpp v81, v78, v17 row_newbcast:6 row_mask:0xf bank_mask:0xf
	v_fmac_f32_dpp v81, v79, v15 row_newbcast:6 row_mask:0xf bank_mask:0xf
	s_nop 0
	s_waitcnt lgkmcnt(1)
	s_waitcnt lgkmcnt(0)
	s_nop 0
	v_mov_b32_e32 v44, v81
	v_min_f32_e32 v45, 0, v44
	v_mul_f32_e64 v44, |v44|, s5
	v_exp_f32_e32 v44, v44
	s_nop 0
	v_add_f32_e32 v44, 1.0, v44
	v_cmp_gt_f32_e32 vcc, s37, v44
	s_nop 1
	v_cndmask_b32_e64 v46, 0, 32, vcc
	v_ldexp_f32 v44, v44, v46
	v_log_f32_e32 v44, v44
	s_nop 0
	v_mul_f32_e32 v46, 0x3f317217, v44
	v_fma_f32 v46, v44, s2, -v46
	v_fmac_f32_e32 v46, 0x3377d1cf, v44
	v_fmac_f32_e32 v46, 0x3f317217, v44
	v_cmp_lt_f32_e64 s[6:7], |v44|, s12
	s_nop 1
	v_cndmask_b32_e64 v44, v44, v46, s[6:7]
	v_cndmask_b32_e32 v46, 0, v232, vcc
	v_sub_f32_e32 v44, v44, v46
	v_sub_f32_e32 v44, v45, v44
	v_fmamk_f32 v44, v44, 0x3d800000, v43
	s_waitcnt lgkmcnt(1)
	s_waitcnt lgkmcnt(0)
	v_mov_b32_e32 v81, v22
	v_fmac_f32_dpp v81, v64, v6 row_newbcast:7 row_mask:0xf bank_mask:0xf
	v_fmac_f32_dpp v81, v65, v8 row_newbcast:7 row_mask:0xf bank_mask:0xf
	v_fmac_f32_dpp v81, v66, v12 row_newbcast:7 row_mask:0xf bank_mask:0xf
	v_fmac_f32_dpp v81, v67, v10 row_newbcast:7 row_mask:0xf bank_mask:0xf
	v_fmac_f32_dpp v81, v68, v7 row_newbcast:7 row_mask:0xf bank_mask:0xf
	v_fmac_f32_dpp v81, v69, v9 row_newbcast:7 row_mask:0xf bank_mask:0xf
	v_fmac_f32_dpp v81, v70, v13 row_newbcast:7 row_mask:0xf bank_mask:0xf
	v_fmac_f32_dpp v81, v71, v11 row_newbcast:7 row_mask:0xf bank_mask:0xf
	v_fmac_f32_dpp v81, v72, v2 row_newbcast:7 row_mask:0xf bank_mask:0xf
	v_fmac_f32_dpp v81, v73, v4 row_newbcast:7 row_mask:0xf bank_mask:0xf
	v_fmac_f32_dpp v81, v74, v16 row_newbcast:7 row_mask:0xf bank_mask:0xf
	v_fmac_f32_dpp v81, v75, v14 row_newbcast:7 row_mask:0xf bank_mask:0xf
	v_fmac_f32_dpp v81, v76, v3 row_newbcast:7 row_mask:0xf bank_mask:0xf
	v_fmac_f32_dpp v81, v77, v5 row_newbcast:7 row_mask:0xf bank_mask:0xf
	v_fmac_f32_dpp v81, v78, v17 row_newbcast:7 row_mask:0xf bank_mask:0xf
	v_fmac_f32_dpp v81, v79, v15 row_newbcast:7 row_mask:0xf bank_mask:0xf
	s_nop 0
	s_waitcnt lgkmcnt(1)
	s_waitcnt lgkmcnt(0)
	s_nop 0
	v_mov_b32_e32 v45, v81
	v_min_f32_e32 v46, 0, v45
	v_mul_f32_e64 v45, |v45|, s5
	v_exp_f32_e32 v45, v45
	s_nop 0
	v_add_f32_e32 v45, 1.0, v45
	v_cmp_gt_f32_e32 vcc, s37, v45
	s_nop 1
	v_cndmask_b32_e64 v47, 0, 32, vcc
	v_ldexp_f32 v45, v45, v47
	v_log_f32_e32 v45, v45
	s_nop 0
	v_mul_f32_e32 v47, 0x3f317217, v45
	v_fma_f32 v47, v45, s2, -v47
	v_fmac_f32_e32 v47, 0x3377d1cf, v45
	v_fmac_f32_e32 v47, 0x3f317217, v45
	v_cmp_lt_f32_e64 s[6:7], |v45|, s12
	s_nop 1
	v_cndmask_b32_e64 v45, v45, v47, s[6:7]
	v_cndmask_b32_e32 v47, 0, v232, vcc
	v_sub_f32_e32 v45, v45, v47
	v_sub_f32_e32 v45, v46, v45
	v_fmamk_f32 v45, v45, 0x3d800000, v44
	s_waitcnt lgkmcnt(1)
	s_waitcnt lgkmcnt(0)
	v_mov_b32_e32 v81, v22
	v_fmac_f32_dpp v81, v64, v6 row_newbcast:8 row_mask:0xf bank_mask:0xf
	v_fmac_f32_dpp v81, v65, v8 row_newbcast:8 row_mask:0xf bank_mask:0xf
	v_fmac_f32_dpp v81, v66, v12 row_newbcast:8 row_mask:0xf bank_mask:0xf
	v_fmac_f32_dpp v81, v67, v10 row_newbcast:8 row_mask:0xf bank_mask:0xf
	v_fmac_f32_dpp v81, v68, v7 row_newbcast:8 row_mask:0xf bank_mask:0xf
	v_fmac_f32_dpp v81, v69, v9 row_newbcast:8 row_mask:0xf bank_mask:0xf
	v_fmac_f32_dpp v81, v70, v13 row_newbcast:8 row_mask:0xf bank_mask:0xf
	v_fmac_f32_dpp v81, v71, v11 row_newbcast:8 row_mask:0xf bank_mask:0xf
	v_fmac_f32_dpp v81, v72, v2 row_newbcast:8 row_mask:0xf bank_mask:0xf
	v_fmac_f32_dpp v81, v73, v4 row_newbcast:8 row_mask:0xf bank_mask:0xf
	v_fmac_f32_dpp v81, v74, v16 row_newbcast:8 row_mask:0xf bank_mask:0xf
	v_fmac_f32_dpp v81, v75, v14 row_newbcast:8 row_mask:0xf bank_mask:0xf
	v_fmac_f32_dpp v81, v76, v3 row_newbcast:8 row_mask:0xf bank_mask:0xf
	v_fmac_f32_dpp v81, v77, v5 row_newbcast:8 row_mask:0xf bank_mask:0xf
	v_fmac_f32_dpp v81, v78, v17 row_newbcast:8 row_mask:0xf bank_mask:0xf
	v_fmac_f32_dpp v81, v79, v15 row_newbcast:8 row_mask:0xf bank_mask:0xf
	s_nop 0
	s_waitcnt lgkmcnt(1)
	s_waitcnt lgkmcnt(0)
	s_nop 0
	v_mov_b32_e32 v46, v81
	v_min_f32_e32 v47, 0, v46
	v_mul_f32_e64 v46, |v46|, s5
	v_exp_f32_e32 v46, v46
	s_nop 0
	v_add_f32_e32 v46, 1.0, v46
	v_cmp_gt_f32_e32 vcc, s37, v46
	s_nop 1
	v_cndmask_b32_e64 v48, 0, 32, vcc
	v_ldexp_f32 v46, v46, v48
	v_log_f32_e32 v46, v46
	s_nop 0
	v_mul_f32_e32 v48, 0x3f317217, v46
	v_fma_f32 v48, v46, s2, -v48
	v_fmac_f32_e32 v48, 0x3377d1cf, v46
	v_fmac_f32_e32 v48, 0x3f317217, v46
	v_cmp_lt_f32_e64 s[6:7], |v46|, s12
	s_nop 1
	v_cndmask_b32_e64 v46, v46, v48, s[6:7]
	v_cndmask_b32_e32 v48, 0, v232, vcc
	v_sub_f32_e32 v46, v46, v48
	v_sub_f32_e32 v46, v47, v46
	v_fmamk_f32 v46, v46, 0x3d800000, v45
	s_waitcnt lgkmcnt(1)
	s_waitcnt lgkmcnt(0)
	v_mov_b32_e32 v81, v22
	v_fmac_f32_dpp v81, v64, v6 row_newbcast:9 row_mask:0xf bank_mask:0xf
	v_fmac_f32_dpp v81, v65, v8 row_newbcast:9 row_mask:0xf bank_mask:0xf
	v_fmac_f32_dpp v81, v66, v12 row_newbcast:9 row_mask:0xf bank_mask:0xf
	v_fmac_f32_dpp v81, v67, v10 row_newbcast:9 row_mask:0xf bank_mask:0xf
	v_fmac_f32_dpp v81, v68, v7 row_newbcast:9 row_mask:0xf bank_mask:0xf
	v_fmac_f32_dpp v81, v69, v9 row_newbcast:9 row_mask:0xf bank_mask:0xf
	v_fmac_f32_dpp v81, v70, v13 row_newbcast:9 row_mask:0xf bank_mask:0xf
	v_fmac_f32_dpp v81, v71, v11 row_newbcast:9 row_mask:0xf bank_mask:0xf
	v_fmac_f32_dpp v81, v72, v2 row_newbcast:9 row_mask:0xf bank_mask:0xf
	v_fmac_f32_dpp v81, v73, v4 row_newbcast:9 row_mask:0xf bank_mask:0xf
	v_fmac_f32_dpp v81, v74, v16 row_newbcast:9 row_mask:0xf bank_mask:0xf
	v_fmac_f32_dpp v81, v75, v14 row_newbcast:9 row_mask:0xf bank_mask:0xf
	v_fmac_f32_dpp v81, v76, v3 row_newbcast:9 row_mask:0xf bank_mask:0xf
	v_fmac_f32_dpp v81, v77, v5 row_newbcast:9 row_mask:0xf bank_mask:0xf
	v_fmac_f32_dpp v81, v78, v17 row_newbcast:9 row_mask:0xf bank_mask:0xf
	v_fmac_f32_dpp v81, v79, v15 row_newbcast:9 row_mask:0xf bank_mask:0xf
	s_nop 0
	s_waitcnt lgkmcnt(1)
	s_waitcnt lgkmcnt(0)
	s_nop 0
	v_mov_b32_e32 v47, v81
	v_min_f32_e32 v48, 0, v47
	v_mul_f32_e64 v47, |v47|, s5
	v_exp_f32_e32 v47, v47
	s_nop 0
	v_add_f32_e32 v47, 1.0, v47
	v_cmp_gt_f32_e32 vcc, s37, v47
	s_nop 1
	v_cndmask_b32_e64 v49, 0, 32, vcc
	v_ldexp_f32 v47, v47, v49
	v_log_f32_e32 v47, v47
	s_nop 0
	v_mul_f32_e32 v49, 0x3f317217, v47
	v_fma_f32 v49, v47, s2, -v49
	v_fmac_f32_e32 v49, 0x3377d1cf, v47
	v_fmac_f32_e32 v49, 0x3f317217, v47
	v_cmp_lt_f32_e64 s[6:7], |v47|, s12
	s_nop 1
	v_cndmask_b32_e64 v47, v47, v49, s[6:7]
	v_cndmask_b32_e32 v49, 0, v232, vcc
	v_sub_f32_e32 v47, v47, v49
	v_sub_f32_e32 v47, v48, v47
	v_fmamk_f32 v47, v47, 0x3d800000, v46
	s_waitcnt lgkmcnt(1)
	s_waitcnt lgkmcnt(0)
	v_mov_b32_e32 v81, v22
	v_fmac_f32_dpp v81, v64, v6 row_newbcast:10 row_mask:0xf bank_mask:0xf
	v_fmac_f32_dpp v81, v65, v8 row_newbcast:10 row_mask:0xf bank_mask:0xf
	v_fmac_f32_dpp v81, v66, v12 row_newbcast:10 row_mask:0xf bank_mask:0xf
	v_fmac_f32_dpp v81, v67, v10 row_newbcast:10 row_mask:0xf bank_mask:0xf
	v_fmac_f32_dpp v81, v68, v7 row_newbcast:10 row_mask:0xf bank_mask:0xf
	v_fmac_f32_dpp v81, v69, v9 row_newbcast:10 row_mask:0xf bank_mask:0xf
	v_fmac_f32_dpp v81, v70, v13 row_newbcast:10 row_mask:0xf bank_mask:0xf
	v_fmac_f32_dpp v81, v71, v11 row_newbcast:10 row_mask:0xf bank_mask:0xf
	v_fmac_f32_dpp v81, v72, v2 row_newbcast:10 row_mask:0xf bank_mask:0xf
	v_fmac_f32_dpp v81, v73, v4 row_newbcast:10 row_mask:0xf bank_mask:0xf
	v_fmac_f32_dpp v81, v74, v16 row_newbcast:10 row_mask:0xf bank_mask:0xf
	v_fmac_f32_dpp v81, v75, v14 row_newbcast:10 row_mask:0xf bank_mask:0xf
	v_fmac_f32_dpp v81, v76, v3 row_newbcast:10 row_mask:0xf bank_mask:0xf
	v_fmac_f32_dpp v81, v77, v5 row_newbcast:10 row_mask:0xf bank_mask:0xf
	v_fmac_f32_dpp v81, v78, v17 row_newbcast:10 row_mask:0xf bank_mask:0xf
	v_fmac_f32_dpp v81, v79, v15 row_newbcast:10 row_mask:0xf bank_mask:0xf
	s_nop 0
	s_waitcnt lgkmcnt(1)
	s_waitcnt lgkmcnt(0)
	s_nop 0
	v_mov_b32_e32 v48, v81
	v_min_f32_e32 v49, 0, v48
	v_mul_f32_e64 v48, |v48|, s5
	v_exp_f32_e32 v48, v48
	s_nop 0
	v_add_f32_e32 v48, 1.0, v48
	v_cmp_gt_f32_e32 vcc, s37, v48
	s_nop 1
	v_cndmask_b32_e64 v50, 0, 32, vcc
	v_ldexp_f32 v48, v48, v50
	v_log_f32_e32 v48, v48
	s_nop 0
	v_mul_f32_e32 v50, 0x3f317217, v48
	v_fma_f32 v50, v48, s2, -v50
	v_fmac_f32_e32 v50, 0x3377d1cf, v48
	v_fmac_f32_e32 v50, 0x3f317217, v48
	v_cmp_lt_f32_e64 s[6:7], |v48|, s12
	s_nop 1
	v_cndmask_b32_e64 v48, v48, v50, s[6:7]
	v_cndmask_b32_e32 v50, 0, v232, vcc
	v_sub_f32_e32 v48, v48, v50
	v_sub_f32_e32 v48, v49, v48
	v_fmamk_f32 v48, v48, 0x3d800000, v47
	s_waitcnt lgkmcnt(1)
	s_waitcnt lgkmcnt(0)
	v_mov_b32_e32 v81, v22
	v_fmac_f32_dpp v81, v64, v6 row_newbcast:11 row_mask:0xf bank_mask:0xf
	v_fmac_f32_dpp v81, v65, v8 row_newbcast:11 row_mask:0xf bank_mask:0xf
	v_fmac_f32_dpp v81, v66, v12 row_newbcast:11 row_mask:0xf bank_mask:0xf
	v_fmac_f32_dpp v81, v67, v10 row_newbcast:11 row_mask:0xf bank_mask:0xf
	v_fmac_f32_dpp v81, v68, v7 row_newbcast:11 row_mask:0xf bank_mask:0xf
	v_fmac_f32_dpp v81, v69, v9 row_newbcast:11 row_mask:0xf bank_mask:0xf
	v_fmac_f32_dpp v81, v70, v13 row_newbcast:11 row_mask:0xf bank_mask:0xf
	v_fmac_f32_dpp v81, v71, v11 row_newbcast:11 row_mask:0xf bank_mask:0xf
	v_fmac_f32_dpp v81, v72, v2 row_newbcast:11 row_mask:0xf bank_mask:0xf
	v_fmac_f32_dpp v81, v73, v4 row_newbcast:11 row_mask:0xf bank_mask:0xf
	v_fmac_f32_dpp v81, v74, v16 row_newbcast:11 row_mask:0xf bank_mask:0xf
	v_fmac_f32_dpp v81, v75, v14 row_newbcast:11 row_mask:0xf bank_mask:0xf
	v_fmac_f32_dpp v81, v76, v3 row_newbcast:11 row_mask:0xf bank_mask:0xf
	v_fmac_f32_dpp v81, v77, v5 row_newbcast:11 row_mask:0xf bank_mask:0xf
	v_fmac_f32_dpp v81, v78, v17 row_newbcast:11 row_mask:0xf bank_mask:0xf
	v_fmac_f32_dpp v81, v79, v15 row_newbcast:11 row_mask:0xf bank_mask:0xf
	s_nop 0
	s_waitcnt lgkmcnt(1)
	s_waitcnt lgkmcnt(0)
	s_nop 0
	v_mov_b32_e32 v49, v81
	v_min_f32_e32 v50, 0, v49
	v_mul_f32_e64 v49, |v49|, s5
	v_exp_f32_e32 v49, v49
	s_nop 0
	v_add_f32_e32 v49, 1.0, v49
	v_cmp_gt_f32_e32 vcc, s37, v49
	s_nop 1
	v_cndmask_b32_e64 v51, 0, 32, vcc
	v_ldexp_f32 v49, v49, v51
	v_log_f32_e32 v49, v49
	s_nop 0
	v_mul_f32_e32 v51, 0x3f317217, v49
	v_fma_f32 v51, v49, s2, -v51
	v_fmac_f32_e32 v51, 0x3377d1cf, v49
	v_fmac_f32_e32 v51, 0x3f317217, v49
	v_cmp_lt_f32_e64 s[6:7], |v49|, s12
	s_nop 1
	v_cndmask_b32_e64 v49, v49, v51, s[6:7]
	v_cndmask_b32_e32 v51, 0, v232, vcc
	v_sub_f32_e32 v49, v49, v51
	v_sub_f32_e32 v49, v50, v49
	v_fmamk_f32 v49, v49, 0x3d800000, v48
	s_waitcnt lgkmcnt(1)
	s_waitcnt lgkmcnt(0)
	v_mov_b32_e32 v81, v22
	v_fmac_f32_dpp v81, v64, v6 row_newbcast:12 row_mask:0xf bank_mask:0xf
	v_fmac_f32_dpp v81, v65, v8 row_newbcast:12 row_mask:0xf bank_mask:0xf
	v_fmac_f32_dpp v81, v66, v12 row_newbcast:12 row_mask:0xf bank_mask:0xf
	v_fmac_f32_dpp v81, v67, v10 row_newbcast:12 row_mask:0xf bank_mask:0xf
	v_fmac_f32_dpp v81, v68, v7 row_newbcast:12 row_mask:0xf bank_mask:0xf
	v_fmac_f32_dpp v81, v69, v9 row_newbcast:12 row_mask:0xf bank_mask:0xf
	v_fmac_f32_dpp v81, v70, v13 row_newbcast:12 row_mask:0xf bank_mask:0xf
	v_fmac_f32_dpp v81, v71, v11 row_newbcast:12 row_mask:0xf bank_mask:0xf
	v_fmac_f32_dpp v81, v72, v2 row_newbcast:12 row_mask:0xf bank_mask:0xf
	v_fmac_f32_dpp v81, v73, v4 row_newbcast:12 row_mask:0xf bank_mask:0xf
	v_fmac_f32_dpp v81, v74, v16 row_newbcast:12 row_mask:0xf bank_mask:0xf
	v_fmac_f32_dpp v81, v75, v14 row_newbcast:12 row_mask:0xf bank_mask:0xf
	v_fmac_f32_dpp v81, v76, v3 row_newbcast:12 row_mask:0xf bank_mask:0xf
	v_fmac_f32_dpp v81, v77, v5 row_newbcast:12 row_mask:0xf bank_mask:0xf
	v_fmac_f32_dpp v81, v78, v17 row_newbcast:12 row_mask:0xf bank_mask:0xf
	v_fmac_f32_dpp v81, v79, v15 row_newbcast:12 row_mask:0xf bank_mask:0xf
	s_nop 0
	s_waitcnt lgkmcnt(1)
	s_waitcnt lgkmcnt(0)
	s_nop 0
	v_mov_b32_e32 v50, v81
	v_min_f32_e32 v51, 0, v50
	v_mul_f32_e64 v50, |v50|, s5
	v_exp_f32_e32 v50, v50
	s_nop 0
	v_add_f32_e32 v50, 1.0, v50
	v_cmp_gt_f32_e32 vcc, s37, v50
	s_nop 1
	v_cndmask_b32_e64 v52, 0, 32, vcc
	v_ldexp_f32 v50, v50, v52
	v_log_f32_e32 v50, v50
	s_nop 0
	v_mul_f32_e32 v52, 0x3f317217, v50
	v_fma_f32 v52, v50, s2, -v52
	v_fmac_f32_e32 v52, 0x3377d1cf, v50
	v_fmac_f32_e32 v52, 0x3f317217, v50
	v_cmp_lt_f32_e64 s[6:7], |v50|, s12
	s_nop 1
	v_cndmask_b32_e64 v50, v50, v52, s[6:7]
	v_cndmask_b32_e32 v52, 0, v232, vcc
	v_sub_f32_e32 v50, v50, v52
	v_sub_f32_e32 v50, v51, v50
	v_fmamk_f32 v50, v50, 0x3d800000, v49
	s_waitcnt lgkmcnt(1)
	s_waitcnt lgkmcnt(0)
	v_mov_b32_e32 v81, v22
	v_fmac_f32_dpp v81, v64, v6 row_newbcast:13 row_mask:0xf bank_mask:0xf
	v_fmac_f32_dpp v81, v65, v8 row_newbcast:13 row_mask:0xf bank_mask:0xf
	v_fmac_f32_dpp v81, v66, v12 row_newbcast:13 row_mask:0xf bank_mask:0xf
	v_fmac_f32_dpp v81, v67, v10 row_newbcast:13 row_mask:0xf bank_mask:0xf
	v_fmac_f32_dpp v81, v68, v7 row_newbcast:13 row_mask:0xf bank_mask:0xf
	v_fmac_f32_dpp v81, v69, v9 row_newbcast:13 row_mask:0xf bank_mask:0xf
	v_fmac_f32_dpp v81, v70, v13 row_newbcast:13 row_mask:0xf bank_mask:0xf
	v_fmac_f32_dpp v81, v71, v11 row_newbcast:13 row_mask:0xf bank_mask:0xf
	v_fmac_f32_dpp v81, v72, v2 row_newbcast:13 row_mask:0xf bank_mask:0xf
	v_fmac_f32_dpp v81, v73, v4 row_newbcast:13 row_mask:0xf bank_mask:0xf
	v_fmac_f32_dpp v81, v74, v16 row_newbcast:13 row_mask:0xf bank_mask:0xf
	v_fmac_f32_dpp v81, v75, v14 row_newbcast:13 row_mask:0xf bank_mask:0xf
	v_fmac_f32_dpp v81, v76, v3 row_newbcast:13 row_mask:0xf bank_mask:0xf
	v_fmac_f32_dpp v81, v77, v5 row_newbcast:13 row_mask:0xf bank_mask:0xf
	v_fmac_f32_dpp v81, v78, v17 row_newbcast:13 row_mask:0xf bank_mask:0xf
	v_fmac_f32_dpp v81, v79, v15 row_newbcast:13 row_mask:0xf bank_mask:0xf
	s_nop 0
	s_waitcnt lgkmcnt(1)
	s_waitcnt lgkmcnt(0)
	s_nop 0
	v_mov_b32_e32 v51, v81
	v_min_f32_e32 v52, 0, v51
	v_mul_f32_e64 v51, |v51|, s5
	v_exp_f32_e32 v51, v51
	s_nop 0
	v_add_f32_e32 v51, 1.0, v51
	v_cmp_gt_f32_e32 vcc, s37, v51
	s_nop 1
	v_cndmask_b32_e64 v53, 0, 32, vcc
	v_ldexp_f32 v51, v51, v53
	v_log_f32_e32 v51, v51
	s_nop 0
	v_mul_f32_e32 v53, 0x3f317217, v51
	v_fma_f32 v53, v51, s2, -v53
	v_fmac_f32_e32 v53, 0x3377d1cf, v51
	v_fmac_f32_e32 v53, 0x3f317217, v51
	v_cmp_lt_f32_e64 s[6:7], |v51|, s12
	s_nop 1
	v_cndmask_b32_e64 v51, v51, v53, s[6:7]
	v_cndmask_b32_e32 v53, 0, v232, vcc
	v_sub_f32_e32 v51, v51, v53
	v_sub_f32_e32 v51, v52, v51
	v_fmamk_f32 v51, v51, 0x3d800000, v50
	s_waitcnt lgkmcnt(1)
	s_waitcnt lgkmcnt(0)
	v_mov_b32_e32 v81, v22
	v_fmac_f32_dpp v81, v64, v6 row_newbcast:14 row_mask:0xf bank_mask:0xf
	v_fmac_f32_dpp v81, v65, v8 row_newbcast:14 row_mask:0xf bank_mask:0xf
	v_fmac_f32_dpp v81, v66, v12 row_newbcast:14 row_mask:0xf bank_mask:0xf
	v_fmac_f32_dpp v81, v67, v10 row_newbcast:14 row_mask:0xf bank_mask:0xf
	v_fmac_f32_dpp v81, v68, v7 row_newbcast:14 row_mask:0xf bank_mask:0xf
	v_fmac_f32_dpp v81, v69, v9 row_newbcast:14 row_mask:0xf bank_mask:0xf
	v_fmac_f32_dpp v81, v70, v13 row_newbcast:14 row_mask:0xf bank_mask:0xf
	v_fmac_f32_dpp v81, v71, v11 row_newbcast:14 row_mask:0xf bank_mask:0xf
	v_fmac_f32_dpp v81, v72, v2 row_newbcast:14 row_mask:0xf bank_mask:0xf
	v_fmac_f32_dpp v81, v73, v4 row_newbcast:14 row_mask:0xf bank_mask:0xf
	v_fmac_f32_dpp v81, v74, v16 row_newbcast:14 row_mask:0xf bank_mask:0xf
	v_fmac_f32_dpp v81, v75, v14 row_newbcast:14 row_mask:0xf bank_mask:0xf
	v_fmac_f32_dpp v81, v76, v3 row_newbcast:14 row_mask:0xf bank_mask:0xf
	v_fmac_f32_dpp v81, v77, v5 row_newbcast:14 row_mask:0xf bank_mask:0xf
	v_fmac_f32_dpp v81, v78, v17 row_newbcast:14 row_mask:0xf bank_mask:0xf
	v_fmac_f32_dpp v81, v79, v15 row_newbcast:14 row_mask:0xf bank_mask:0xf
	s_nop 0
	s_waitcnt lgkmcnt(1)
	s_waitcnt lgkmcnt(0)
	s_nop 0
	v_mov_b32_e32 v52, v81
	v_min_f32_e32 v53, 0, v52
	v_mul_f32_e64 v52, |v52|, s5
	v_exp_f32_e32 v52, v52
	s_nop 0
	v_add_f32_e32 v52, 1.0, v52
	v_cmp_gt_f32_e32 vcc, s37, v52
	s_nop 1
	v_cndmask_b32_e64 v54, 0, 32, vcc
	v_ldexp_f32 v52, v52, v54
	v_log_f32_e32 v52, v52
	s_nop 0
	v_mul_f32_e32 v54, 0x3f317217, v52
	v_fma_f32 v54, v52, s2, -v54
	v_fmac_f32_e32 v54, 0x3377d1cf, v52
	v_fmac_f32_e32 v54, 0x3f317217, v52
	v_cmp_lt_f32_e64 s[6:7], |v52|, s12
	s_nop 1
	v_cndmask_b32_e64 v52, v52, v54, s[6:7]
	v_cndmask_b32_e32 v54, 0, v232, vcc
	v_sub_f32_e32 v52, v52, v54
	v_sub_f32_e32 v52, v53, v52
	v_fmamk_f32 v62, v52, 0x3d800000, v51
	s_waitcnt lgkmcnt(1)
	s_waitcnt lgkmcnt(0)
	v_mov_b32_e32 v81, v22
	v_fmac_f32_dpp v81, v64, v6 row_newbcast:15 row_mask:0xf bank_mask:0xf
	v_fmac_f32_dpp v81, v65, v8 row_newbcast:15 row_mask:0xf bank_mask:0xf
	v_fmac_f32_dpp v81, v66, v12 row_newbcast:15 row_mask:0xf bank_mask:0xf
	v_fmac_f32_dpp v81, v67, v10 row_newbcast:15 row_mask:0xf bank_mask:0xf
	v_fmac_f32_dpp v81, v68, v7 row_newbcast:15 row_mask:0xf bank_mask:0xf
	v_fmac_f32_dpp v81, v69, v9 row_newbcast:15 row_mask:0xf bank_mask:0xf
	v_fmac_f32_dpp v81, v70, v13 row_newbcast:15 row_mask:0xf bank_mask:0xf
	v_fmac_f32_dpp v81, v71, v11 row_newbcast:15 row_mask:0xf bank_mask:0xf
	v_fmac_f32_dpp v81, v72, v2 row_newbcast:15 row_mask:0xf bank_mask:0xf
	v_fmac_f32_dpp v81, v73, v4 row_newbcast:15 row_mask:0xf bank_mask:0xf
	v_fmac_f32_dpp v81, v74, v16 row_newbcast:15 row_mask:0xf bank_mask:0xf
	v_fmac_f32_dpp v81, v75, v14 row_newbcast:15 row_mask:0xf bank_mask:0xf
	v_fmac_f32_dpp v81, v76, v3 row_newbcast:15 row_mask:0xf bank_mask:0xf
	v_fmac_f32_dpp v81, v77, v5 row_newbcast:15 row_mask:0xf bank_mask:0xf
	v_fmac_f32_dpp v81, v78, v17 row_newbcast:15 row_mask:0xf bank_mask:0xf
	v_fmac_f32_dpp v81, v79, v15 row_newbcast:15 row_mask:0xf bank_mask:0xf
	s_nop 0
	s_nop 0
	s_waitcnt lgkmcnt(1)
	s_waitcnt lgkmcnt(0)
	s_nop 0
	v_lshlrev_b32_e32 v13, 16, v23
	v_mov_b32_e32 v2, v81
	v_min_f32_e32 v3, 0, v2
	v_mul_f32_e64 v2, |v2|, s5
	v_exp_f32_e32 v2, v2
	v_lshlrev_b32_e32 v23, 16, v30
	v_lshlrev_b32_e32 v12, 16, v24
	v_lshlrev_b32_e32 v24, 16, v31
	v_add_f32_e32 v2, 1.0, v2
	v_cmp_gt_f32_e32 vcc, s37, v2
	v_lshlrev_b32_e32 v15, 16, v26
	v_lshlrev_b32_e32 v14, 16, v25
	v_cndmask_b32_e64 v4, 0, 32, vcc
	v_ldexp_f32 v2, v2, v4
	v_log_f32_e32 v2, v2
	v_lshlrev_b32_e32 v17, 16, v28
	v_lshlrev_b32_e32 v16, 16, v27
	v_lshlrev_b32_e32 v22, 16, v29
	v_mul_f32_e32 v4, 0x3f317217, v2
	v_fma_f32 v4, v2, s2, -v4
	v_fmac_f32_e32 v4, 0x3377d1cf, v2
	v_fmac_f32_e32 v4, 0x3f317217, v2
	v_cmp_lt_f32_e64 s[6:7], |v2|, s12
	v_lshlrev_b32_e32 v25, 16, v32
	v_lshlrev_b32_e32 v27, 16, v34
	v_cndmask_b32_e64 v2, v2, v4, s[6:7]
	v_cndmask_b32_e32 v4, 0, v232, vcc
	v_sub_f32_e32 v2, v2, v4
	v_sub_f32_e32 v2, v3, v2
	v_fmamk_f32 v3, v2, 0x3d800000, v62
	v_lshl_add_u32 v2, v18, 2, 0
	ds_write_b32 v2, v3 offset:4096
	v_add_u32_e32 v2, 0, v208
	s_waitcnt lgkmcnt(0)
	s_barrier
	ds_read2st64_b32 v[4:5], v2 offset0:16 offset1:18
	ds_read2st64_b32 v[6:7], v2 offset0:20 offset1:22
	v_cmp_lt_i32_e64 s[6:7], 1, v1
	v_cmp_lt_i32_e32 vcc, 0, v1
	v_lshlrev_b32_e32 v26, 16, v33
	s_waitcnt lgkmcnt(1)
	v_cndmask_b32_e64 v8, 0, v5, s[6:7]
	v_cmp_lt_i32_e64 s[6:7], 2, v1
	v_add_f32_e32 v30, 0, v4
	s_waitcnt lgkmcnt(0)
	v_mov_b32_e32 v10, v6
	v_cndmask_b32_e64 v9, 0, v6, s[6:7]
	v_cmp_lt_i32_e64 s[6:7], 3, v1
	v_cndmask_b32_e32 v1, 0, v30, vcc
	v_add_f32_e32 v31, v1, v8
	v_mov_b32_e32 v8, v5
	v_cndmask_b32_e64 v11, 0, v7, s[6:7]
	v_pk_add_f32 v[4:5], v[30:31], v[8:9]
	v_mov_b32_e32 v2, v7
	v_pk_add_f32 v[10:11], v[4:5], v[10:11]
	v_lshlrev_b32_e32 v29, 16, v36
	v_add_f32_e32 v1, v37, v11
	v_pk_add_f32 v[2:3], v[10:11], v[2:3]
	v_lshlrev_b32_e32 v28, 16, v35
	v_sub_f32_e32 v1, v2, v1
	v_mul_f32_e32 v1, 0x3fb8aa3b, v1
	v_exp_f32_e32 v4, v1
	v_add_f32_e32 v1, v39, v11
	v_sub_f32_e32 v1, v2, v1
	v_mul_f32_e32 v1, 0x3fb8aa3b, v1
	v_exp_f32_e32 v5, v1
	v_add_f32_e32 v1, v40, v11
	v_sub_f32_e32 v1, v2, v1
	v_mul_f32_e32 v1, 0x3fb8aa3b, v1
	v_exp_f32_e32 v6, v1
	v_add_f32_e32 v1, v41, v11
	v_sub_f32_e32 v1, v2, v1
	v_mul_f32_e32 v1, 0x3fb8aa3b, v1
	v_exp_f32_e32 v7, v1
	v_add_f32_e32 v1, v42, v11
	v_sub_f32_e32 v1, v2, v1
	v_pk_mul_f32 v[4:5], v[4:5], v[12:13]
	v_pk_mul_f32 v[6:7], v[6:7], v[14:15]
	v_mul_f32_e32 v1, 0x3fb8aa3b, v1
	v_cvt_pk_bf16_f32 v4, v4, v5
	v_cvt_pk_bf16_f32 v5, v6, v7
	v_exp_f32_e32 v6, v1
	v_add_f32_e32 v1, v43, v11
	v_sub_f32_e32 v1, v2, v1
	v_mul_f32_e32 v1, 0x3fb8aa3b, v1
	v_exp_f32_e32 v7, v1
	v_add_f32_e32 v1, v44, v11
	v_sub_f32_e32 v1, v2, v1
	v_mul_f32_e32 v1, 0x3fb8aa3b, v1
	v_exp_f32_e32 v8, v1
	v_add_f32_e32 v1, v45, v11
	v_sub_f32_e32 v1, v2, v1
	v_mul_f32_e32 v1, 0x3fb8aa3b, v1
	v_exp_f32_e32 v9, v1
	v_add_f32_e32 v1, v46, v11
	v_sub_f32_e32 v1, v2, v1
	v_pk_mul_f32 v[6:7], v[6:7], v[16:17]
	v_pk_mul_f32 v[8:9], v[8:9], v[22:23]
	v_mul_f32_e32 v1, 0x3fb8aa3b, v1
	v_cvt_pk_bf16_f32 v6, v6, v7
	v_cvt_pk_bf16_f32 v7, v8, v9
	v_exp_f32_e32 v8, v1
	v_add_f32_e32 v1, v47, v11
	v_sub_f32_e32 v1, v2, v1
	v_mul_f32_e32 v1, 0x3fb8aa3b, v1
	v_exp_f32_e32 v9, v1
	v_add_f32_e32 v1, v48, v11
	v_sub_f32_e32 v1, v2, v1
	v_mul_f32_e32 v1, 0x3fb8aa3b, v1
	v_exp_f32_e32 v12, v1
	v_add_f32_e32 v1, v49, v11
	v_sub_f32_e32 v1, v2, v1
	v_mul_f32_e32 v1, 0x3fb8aa3b, v1
	v_exp_f32_e32 v13, v1
	v_add_f32_e32 v1, v50, v11
	v_sub_f32_e32 v1, v2, v1
	v_pk_mul_f32 v[8:9], v[8:9], v[24:25]
	v_pk_mul_f32 v[12:13], v[12:13], v[26:27]
	v_mul_f32_e32 v1, 0x3fb8aa3b, v1
	v_cvt_pk_bf16_f32 v8, v8, v9
	v_cvt_pk_bf16_f32 v9, v12, v13
	v_exp_f32_e32 v12, v1
	v_add_f32_e32 v1, v51, v11
	v_sub_f32_e32 v1, v2, v1
	v_mul_f32_e32 v1, 0x3fb8aa3b, v1
	v_exp_f32_e32 v13, v1
	v_add_f32_e32 v1, v11, v62
	v_sub_f32_e32 v1, v2, v1
	v_mul_f32_e32 v1, 0x3fb8aa3b, v1
	v_pk_mul_f32 v[12:13], v[12:13], v[28:29]
	v_lshlrev_b32_e32 v15, 16, v21
	v_cvt_pk_bf16_f32 v10, v12, v13
	v_exp_f32_e32 v12, v1
	v_sub_f32_e32 v1, v2, v3
	v_mul_f32_e32 v1, 0x3fb8aa3b, v1
	v_exp_f32_e32 v13, v1
	v_lshlrev_b32_e32 v14, 16, v20
	v_ashrrev_i32_e32 v1, 31, v0
	v_cmp_gt_u32_e32 vcc, s4, v18
	v_pk_mul_f32 v[12:13], v[12:13], v[14:15]
	s_nop 0
	v_cvt_pk_bf16_f32 v11, v12, v13
	v_lshlrev_b32_e32 v12, 7, v19
	v_mov_b32_e32 v13, v209
	v_lshl_add_u64 v[0:1], v[0:1], 1, v[12:13]
	v_lshl_add_u64 v[0:1], s[50:51], 0, v[0:1]
	v_lshl_add_u64 v[0:1], v[0:1], 0, s[94:95]
	global_store_dwordx4 v[0:1], v[4:7], off offset:-16
	global_store_dwordx4 v[0:1], v[8:11], off
	s_and_saveexec_b64 s[6:7], vcc
	s_cbranch_execz .LBB0_984
	v_mul_f32_e32 v0, 0x3fb8aa3b, v2
	v_exp_f32_e32 v2, v0
	v_lshl_add_u64 v[0:1], s[50:51], 0, v[208:209]
	v_lshl_add_u64 v[0:1], v[0:1], 0, s[90:91]
	global_store_dword v[0:1], v2, off
	s_branch .LBB0_984
